# P1+P7: all bias vectors loaded at the top of each unit before the K loop; epilogue has no vmcnt waits
# speedup vs baseline: 1.0076x; 1.0076x over previous
.LBB0_189:
	v_lshlrev_b32_e32 v232, 3, v153
	v_add_u32_e32 v232, s70, v232
	v_ashrrev_i32_e32 v233, 31, v232
	v_lshl_add_u64 v[232:233], v[232:233], 2, s[58:59]
	s_cmp_eq_u64 s[58:59], 0
	s_cbranch_scc1 .Lbt_null1
	global_load_dwordx4 v[216:219], v[232:233], off
	global_load_dwordx4 v[220:223], v[232:233], off offset:16
	global_load_dwordx4 v[224:227], v[232:233], off offset:512
	global_load_dwordx4 v[228:231], v[232:233], off offset:528
	s_branch .Lbt_done1
.Lbt_null1:
	v_mov_b32_e32 v216, 0
	v_mov_b32_e32 v217, 0
	v_mov_b32_e32 v218, 0
	v_mov_b32_e32 v219, 0
	v_mov_b32_e32 v220, 0
	v_mov_b32_e32 v221, 0
	v_mov_b32_e32 v222, 0
	v_mov_b32_e32 v223, 0
	v_mov_b32_e32 v224, 0
	v_mov_b32_e32 v225, 0
	v_mov_b32_e32 v226, 0
	v_mov_b32_e32 v227, 0
	v_mov_b32_e32 v228, 0
	v_mov_b32_e32 v229, 0
	v_mov_b32_e32 v230, 0
	v_mov_b32_e32 v231, 0

.LBB0_193:
	v_mov_b32_e32 v130, v153
	v_mov_b32_e32 v149, v152
	v_lshlrev_b32_e32 v148, 3, v130
	v_add_u32_e32 v150, s70, v148
	v_ashrrev_i32_e32 v151, 31, v150
	v_add_u32_e32 v158, s41, v149
	v_ashrrev_i32_e32 v159, 31, v158
	v_lshlrev_b64 v[158:159], 11, v[158:159]
	v_lshl_add_u64 v[158:159], s[60:61], 0, v[158:159]
	v_lshl_add_u64 v[158:159], v[158:159], 0, s[20:21]
	v_ashrrev_i32_e32 v149, 31, v148
	v_lshl_add_u64 v[148:149], v[148:149], 1, v[158:159]
	v_pk_add_f32 v[128:129], v[128:129], v[218:219]
	v_pk_add_f32 v[126:127], v[126:127], v[216:217]
	v_pk_add_f32 v[158:159], v[124:125], v[222:223]
	v_pk_add_f32 v[124:125], v[122:123], v[220:221]
	v_cvt_pk_bf16_f32 v122, v126, v127
	v_cvt_pk_bf16_f32 v123, v128, v129
	v_pk_add_f32 v[118:119], v[118:119], v[216:217]
	v_pk_add_f32 v[114:115], v[114:115], v[220:221]
	v_cvt_pk_bf16_f32 v124, v124, v125
	v_cvt_pk_bf16_f32 v125, v158, v159
	global_store_dwordx4 v[148:149], v[122:125], off
	v_pk_add_f32 v[120:121], v[120:121], v[218:219]
	v_pk_add_f32 v[110:111], v[110:111], v[216:217]
	v_pk_add_f32 v[122:123], v[116:117], v[222:223]
	v_cvt_pk_bf16_f32 v116, v118, v119
	v_cvt_pk_bf16_f32 v117, v120, v121
	v_cvt_pk_bf16_f32 v118, v114, v115
	v_add_co_u32_e32 v114, vcc, s72, v148
	v_pk_add_f32 v[106:107], v[106:107], v[220:221]
	s_nop 0
	v_addc_co_u32_e32 v115, vcc, 0, v149, vcc
	v_cvt_pk_bf16_f32 v119, v122, v123
	global_store_dwordx4 v[114:115], v[116:119], off
	v_pk_add_f32 v[112:113], v[112:113], v[218:219]
	v_pk_add_f32 v[102:103], v[102:103], v[216:217]
	v_pk_add_f32 v[116:117], v[108:109], v[222:223]
	v_cvt_pk_bf16_f32 v108, v110, v111
	v_cvt_pk_bf16_f32 v109, v112, v113
	v_cvt_pk_bf16_f32 v110, v106, v107
	v_add_co_u32_e32 v106, vcc, s27, v148
	v_pk_add_f32 v[98:99], v[98:99], v[220:221]
	s_nop 0
	v_addc_co_u32_e32 v107, vcc, 0, v149, vcc
	v_cvt_pk_bf16_f32 v111, v116, v117
	global_store_dwordx4 v[106:107], v[108:111], off
	v_pk_add_f32 v[104:105], v[104:105], v[218:219]
	v_pk_add_f32 v[94:95], v[94:95], v[216:217]
	v_pk_add_f32 v[108:109], v[100:101], v[222:223]
	v_cvt_pk_bf16_f32 v100, v102, v103
	v_cvt_pk_bf16_f32 v101, v104, v105
	v_cvt_pk_bf16_f32 v102, v98, v99
	v_add_co_u32_e32 v98, vcc, s71, v148
	v_pk_add_f32 v[90:91], v[90:91], v[220:221]
	s_nop 0
	v_addc_co_u32_e32 v99, vcc, 0, v149, vcc
	v_cvt_pk_bf16_f32 v103, v108, v109
	global_store_dwordx4 v[98:99], v[100:103], off
	v_pk_add_f32 v[96:97], v[96:97], v[218:219]
	v_pk_add_f32 v[86:87], v[86:87], v[216:217]
	v_pk_add_f32 v[100:101], v[92:93], v[222:223]
	v_cvt_pk_bf16_f32 v92, v94, v95
	v_cvt_pk_bf16_f32 v93, v96, v97
	v_cvt_pk_bf16_f32 v94, v90, v91
	v_add_co_u32_e32 v90, vcc, s77, v148
	v_pk_add_f32 v[82:83], v[82:83], v[220:221]
	s_nop 0
	v_addc_co_u32_e32 v91, vcc, 0, v149, vcc
	v_cvt_pk_bf16_f32 v95, v100, v101
	global_store_dwordx4 v[90:91], v[92:95], off
	v_pk_add_f32 v[88:89], v[88:89], v[218:219]
	v_pk_add_f32 v[78:79], v[78:79], v[216:217]
	v_pk_add_f32 v[92:93], v[84:85], v[222:223]
	v_cvt_pk_bf16_f32 v84, v86, v87
	v_cvt_pk_bf16_f32 v85, v88, v89
	v_cvt_pk_bf16_f32 v86, v82, v83
	v_add_co_u32_e32 v82, vcc, s78, v148
	v_pk_add_f32 v[74:75], v[74:75], v[220:221]
	s_nop 0
	v_addc_co_u32_e32 v83, vcc, 0, v149, vcc
	v_cvt_pk_bf16_f32 v87, v92, v93
	global_store_dwordx4 v[82:83], v[84:87], off
	v_pk_add_f32 v[80:81], v[80:81], v[218:219]
	v_pk_add_f32 v[70:71], v[70:71], v[216:217]
	v_pk_add_f32 v[84:85], v[76:77], v[222:223]
	v_cvt_pk_bf16_f32 v76, v78, v79
	v_cvt_pk_bf16_f32 v77, v80, v81
	v_cvt_pk_bf16_f32 v78, v74, v75
	v_add_co_u32_e32 v74, vcc, s79, v148
	v_cvt_pk_bf16_f32 v79, v84, v85
	v_pk_add_f32 v[72:73], v[72:73], v[218:219]
	s_nop 0
	v_addc_co_u32_e32 v75, vcc, 0, v149, vcc
	global_store_dwordx4 v[74:75], v[76:79], off
	s_nop 1
	v_pk_add_f32 v[76:77], v[68:69], v[222:223]
	v_pk_add_f32 v[68:69], v[66:67], v[220:221]
	v_cvt_pk_bf16_f32 v66, v70, v71
	v_add_co_u32_e32 v70, vcc, 0x58000, v148
	v_cvt_pk_bf16_f32 v67, v72, v73
	v_cvt_pk_bf16_f32 v68, v68, v69
	v_cvt_pk_bf16_f32 v69, v76, v77
	v_mov_b32_e32 v72, 0
	s_nop 0
	v_addc_co_u32_e32 v71, vcc, 0, v149, vcc
	global_store_dwordx4 v[70:71], v[66:69], off
	v_pk_add_f32 v[64:65], v[64:65], v[226:227]
	v_pk_add_f32 v[62:63], v[62:63], v[224:225]
	v_pk_add_f32 v[76:77], v[60:61], v[230:231]
	v_pk_add_f32 v[60:61], v[58:59], v[228:229]
	v_cvt_pk_bf16_f32 v58, v62, v63
	v_cvt_pk_bf16_f32 v59, v64, v65
	v_pk_add_f32 v[56:57], v[56:57], v[226:227]
	v_cvt_pk_bf16_f32 v60, v60, v61
	v_cvt_pk_bf16_f32 v61, v76, v77
	global_store_dwordx4 v[148:149], v[58:61], off offset:256
	v_pk_add_f32 v[54:55], v[54:55], v[224:225]
	v_pk_add_f32 v[48:49], v[48:49], v[226:227]
	v_pk_add_f32 v[58:59], v[52:53], v[230:231]
	v_pk_add_f32 v[52:53], v[50:51], v[228:229]
	v_cvt_pk_bf16_f32 v50, v54, v55
	v_cvt_pk_bf16_f32 v51, v56, v57
	v_pk_add_f32 v[46:47], v[46:47], v[224:225]
	v_cvt_pk_bf16_f32 v52, v52, v53
	v_cvt_pk_bf16_f32 v53, v58, v59
	global_store_dwordx4 v[114:115], v[50:53], off offset:256
	v_pk_add_f32 v[40:41], v[40:41], v[226:227]
	v_pk_add_f32 v[38:39], v[38:39], v[224:225]
	v_pk_add_f32 v[50:51], v[44:45], v[230:231]
	v_pk_add_f32 v[44:45], v[42:43], v[228:229]
	v_cvt_pk_bf16_f32 v42, v46, v47
	v_cvt_pk_bf16_f32 v43, v48, v49
	v_pk_add_f32 v[32:33], v[32:33], v[226:227]
	v_cvt_pk_bf16_f32 v44, v44, v45
	v_cvt_pk_bf16_f32 v45, v50, v51
	global_store_dwordx4 v[106:107], v[42:45], off offset:256
	v_pk_add_f32 v[30:31], v[30:31], v[224:225]
	v_pk_add_f32 v[24:25], v[24:25], v[226:227]
	v_pk_add_f32 v[42:43], v[36:37], v[230:231]
	v_pk_add_f32 v[36:37], v[34:35], v[228:229]
	v_cvt_pk_bf16_f32 v34, v38, v39
	v_cvt_pk_bf16_f32 v35, v40, v41
	v_pk_add_f32 v[22:23], v[22:23], v[224:225]
	v_cvt_pk_bf16_f32 v36, v36, v37
	v_cvt_pk_bf16_f32 v37, v42, v43
	global_store_dwordx4 v[98:99], v[34:37], off offset:256
	v_pk_add_f32 v[16:17], v[16:17], v[226:227]
	v_pk_add_f32 v[14:15], v[14:15], v[224:225]
	v_pk_add_f32 v[34:35], v[28:29], v[230:231]
	v_pk_add_f32 v[28:29], v[26:27], v[228:229]
	v_cvt_pk_bf16_f32 v26, v30, v31
	v_cvt_pk_bf16_f32 v27, v32, v33
	v_pk_add_f32 v[6:7], v[6:7], v[224:225]
	v_cvt_pk_bf16_f32 v28, v28, v29
	v_cvt_pk_bf16_f32 v29, v34, v35
	global_store_dwordx4 v[90:91], v[26:29], off offset:256
	v_pk_add_f32 v[8:9], v[8:9], v[226:227]
	s_nop 0
	v_pk_add_f32 v[26:27], v[20:21], v[230:231]
	v_pk_add_f32 v[20:21], v[18:19], v[228:229]
	v_cvt_pk_bf16_f32 v18, v22, v23
	v_cvt_pk_bf16_f32 v19, v24, v25
	s_nop 0
	v_cvt_pk_bf16_f32 v20, v20, v21
	v_cvt_pk_bf16_f32 v21, v26, v27
	global_store_dwordx4 v[82:83], v[18:21], off offset:256
	s_nop 1
	v_pk_add_f32 v[18:19], v[12:13], v[230:231]
	v_pk_add_f32 v[12:13], v[10:11], v[228:229]
	v_cvt_pk_bf16_f32 v10, v14, v15
	v_cvt_pk_bf16_f32 v11, v16, v17
	s_nop 0
	v_cvt_pk_bf16_f32 v12, v12, v13
	v_cvt_pk_bf16_f32 v13, v18, v19
	global_store_dwordx4 v[74:75], v[10:13], off offset:256
	s_nop 1
	v_pk_add_f32 v[10:11], v[4:5], v[230:231]
	v_pk_add_f32 v[4:5], v[2:3], v[228:229]
	v_cvt_pk_bf16_f32 v2, v6, v7
	v_add_co_u32_e32 v6, vcc, 0x58000, v148
	v_cvt_pk_bf16_f32 v3, v8, v9
	v_cvt_pk_bf16_f32 v4, v4, v5
	v_cvt_pk_bf16_f32 v5, v10, v11
	s_nop 1
	v_addc_co_u32_e32 v7, vcc, 0, v149, vcc
	global_store_dwordx4 v[6:7], v[2:5], off offset:256
	s_andn2_b64 vcc, exec, s[8:9]
	s_mov_b64 s[8:9], -1
	s_cbranch_vccnz .LBB0_186
	s_andn2_b64 vcc, exec, s[22:23]
	s_cbranch_vccnz .LBB0_185
	s_barrier
	s_branch .LBB0_185

.LBB0_1048:
	v_lshlrev_b32_e32 v232, 3, v153
	v_add_u32_e32 v232, s75, v232
	v_ashrrev_i32_e32 v233, 31, v232
	v_lshl_add_u64 v[232:233], v[232:233], 2, s[60:61]
	s_cmp_eq_u64 s[60:61], 0
	s_cbranch_scc1 .Lbt_null2
	global_load_dwordx4 v[216:219], v[232:233], off
	global_load_dwordx4 v[220:223], v[232:233], off offset:16
	global_load_dwordx4 v[224:227], v[232:233], off offset:512
	global_load_dwordx4 v[228:231], v[232:233], off offset:528
	s_branch .Lbt_done2

.LBB0_1052:
	v_mov_b32_e32 v130, v153
	v_mov_b32_e32 v149, v152
	v_lshlrev_b32_e32 v148, 3, v130
	v_add_u32_e32 v150, s75, v148
	v_ashrrev_i32_e32 v151, 31, v150
	v_add_u32_e32 v158, s74, v149
	v_ashrrev_i32_e32 v159, 31, v158
	v_lshlrev_b64 v[158:159], 11, v[158:159]
	v_lshl_add_u64 v[158:159], s[62:63], 0, v[158:159]
	v_lshl_add_u64 v[158:159], v[158:159], 0, s[40:41]
	v_ashrrev_i32_e32 v149, 31, v148
	v_lshl_add_u64 v[148:149], v[148:149], 1, v[158:159]
	v_pk_add_f32 v[128:129], v[128:129], v[218:219]
	v_pk_add_f32 v[126:127], v[126:127], v[216:217]
	v_pk_add_f32 v[158:159], v[124:125], v[222:223]
	v_pk_add_f32 v[124:125], v[122:123], v[220:221]
	v_cvt_pk_bf16_f32 v122, v126, v127
	v_cvt_pk_bf16_f32 v123, v128, v129
	v_pk_add_f32 v[118:119], v[118:119], v[216:217]
	v_pk_add_f32 v[114:115], v[114:115], v[220:221]
	s_mov_b32 s0, 0x8000
	v_cvt_pk_bf16_f32 v124, v124, v125
	v_cvt_pk_bf16_f32 v125, v158, v159
	global_store_dwordx4 v[148:149], v[122:125], off
	v_pk_add_f32 v[120:121], v[120:121], v[218:219]
	v_pk_add_f32 v[110:111], v[110:111], v[216:217]
	v_pk_add_f32 v[122:123], v[116:117], v[222:223]
	v_cvt_pk_bf16_f32 v116, v118, v119
	v_cvt_pk_bf16_f32 v117, v120, v121
	v_cvt_pk_bf16_f32 v118, v114, v115
	v_add_co_u32_e32 v114, vcc, s0, v148
	v_pk_add_f32 v[106:107], v[106:107], v[220:221]
	s_nop 0
	v_addc_co_u32_e32 v115, vcc, 0, v149, vcc
	s_mov_b32 s0, 0x10000
	v_cvt_pk_bf16_f32 v119, v122, v123
	global_store_dwordx4 v[114:115], v[116:119], off
	v_pk_add_f32 v[112:113], v[112:113], v[218:219]
	v_pk_add_f32 v[102:103], v[102:103], v[216:217]
	v_pk_add_f32 v[116:117], v[108:109], v[222:223]
	v_cvt_pk_bf16_f32 v108, v110, v111
	v_cvt_pk_bf16_f32 v109, v112, v113
	v_cvt_pk_bf16_f32 v110, v106, v107
	v_add_co_u32_e32 v106, vcc, s0, v148
	v_pk_add_f32 v[98:99], v[98:99], v[220:221]
	s_nop 0
	v_addc_co_u32_e32 v107, vcc, 0, v149, vcc
	s_mov_b32 s0, 0x18000
	v_cvt_pk_bf16_f32 v111, v116, v117
	global_store_dwordx4 v[106:107], v[108:111], off
	v_pk_add_f32 v[104:105], v[104:105], v[218:219]
	v_pk_add_f32 v[94:95], v[94:95], v[216:217]
	v_pk_add_f32 v[108:109], v[100:101], v[222:223]
	v_cvt_pk_bf16_f32 v100, v102, v103
	v_cvt_pk_bf16_f32 v101, v104, v105
	v_cvt_pk_bf16_f32 v102, v98, v99
	v_add_co_u32_e32 v98, vcc, s0, v148
	v_pk_add_f32 v[90:91], v[90:91], v[220:221]
	s_nop 0
	v_addc_co_u32_e32 v99, vcc, 0, v149, vcc
	s_mov_b32 s0, 0x40000
	v_cvt_pk_bf16_f32 v103, v108, v109
	global_store_dwordx4 v[98:99], v[100:103], off
	v_pk_add_f32 v[96:97], v[96:97], v[218:219]
	v_pk_add_f32 v[86:87], v[86:87], v[216:217]
	v_pk_add_f32 v[100:101], v[92:93], v[222:223]
	v_cvt_pk_bf16_f32 v92, v94, v95
	v_cvt_pk_bf16_f32 v93, v96, v97
	v_cvt_pk_bf16_f32 v94, v90, v91
	v_add_co_u32_e32 v90, vcc, s0, v148
	v_pk_add_f32 v[82:83], v[82:83], v[220:221]
	s_nop 0
	v_addc_co_u32_e32 v91, vcc, 0, v149, vcc
	v_cvt_pk_bf16_f32 v95, v100, v101
	global_store_dwordx4 v[90:91], v[92:95], off
	v_pk_add_f32 v[88:89], v[88:89], v[218:219]
	v_pk_add_f32 v[78:79], v[78:79], v[216:217]
	v_pk_add_f32 v[92:93], v[84:85], v[222:223]
	v_cvt_pk_bf16_f32 v84, v86, v87
	v_cvt_pk_bf16_f32 v85, v88, v89
	v_cvt_pk_bf16_f32 v86, v82, v83
	v_add_co_u32_e32 v82, vcc, s80, v148
	v_pk_add_f32 v[74:75], v[74:75], v[220:221]
	s_nop 0
	v_addc_co_u32_e32 v83, vcc, 0, v149, vcc
	v_cvt_pk_bf16_f32 v87, v92, v93
	global_store_dwordx4 v[82:83], v[84:87], off
	v_pk_add_f32 v[80:81], v[80:81], v[218:219]
	v_pk_add_f32 v[70:71], v[70:71], v[216:217]
	v_pk_add_f32 v[84:85], v[76:77], v[222:223]
	v_cvt_pk_bf16_f32 v76, v78, v79
	v_cvt_pk_bf16_f32 v77, v80, v81
	v_cvt_pk_bf16_f32 v78, v74, v75
	v_add_co_u32_e32 v74, vcc, s81, v148
	v_cvt_pk_bf16_f32 v79, v84, v85
	v_pk_add_f32 v[72:73], v[72:73], v[218:219]
	s_nop 0
	v_addc_co_u32_e32 v75, vcc, 0, v149, vcc
	global_store_dwordx4 v[74:75], v[76:79], off
	s_nop 1
	v_pk_add_f32 v[76:77], v[68:69], v[222:223]
	v_pk_add_f32 v[68:69], v[66:67], v[220:221]
	v_cvt_pk_bf16_f32 v66, v70, v71
	v_add_co_u32_e32 v70, vcc, 0x58000, v148
	v_cvt_pk_bf16_f32 v67, v72, v73
	v_cvt_pk_bf16_f32 v68, v68, v69
	v_cvt_pk_bf16_f32 v69, v76, v77
	v_mov_b32_e32 v72, 0
	s_nop 0
	v_addc_co_u32_e32 v71, vcc, 0, v149, vcc
	global_store_dwordx4 v[70:71], v[66:69], off
	v_pk_add_f32 v[64:65], v[64:65], v[226:227]
	v_pk_add_f32 v[62:63], v[62:63], v[224:225]
	v_pk_add_f32 v[76:77], v[60:61], v[230:231]
	v_pk_add_f32 v[60:61], v[58:59], v[228:229]
	v_cvt_pk_bf16_f32 v58, v62, v63
	v_cvt_pk_bf16_f32 v59, v64, v65
	v_pk_add_f32 v[56:57], v[56:57], v[226:227]
	v_cvt_pk_bf16_f32 v60, v60, v61
	v_cvt_pk_bf16_f32 v61, v76, v77
	global_store_dwordx4 v[148:149], v[58:61], off offset:256
	v_pk_add_f32 v[54:55], v[54:55], v[224:225]
	v_pk_add_f32 v[48:49], v[48:49], v[226:227]
	v_pk_add_f32 v[58:59], v[52:53], v[230:231]
	v_pk_add_f32 v[52:53], v[50:51], v[228:229]
	v_cvt_pk_bf16_f32 v50, v54, v55
	v_cvt_pk_bf16_f32 v51, v56, v57
	v_pk_add_f32 v[46:47], v[46:47], v[224:225]
	v_cvt_pk_bf16_f32 v52, v52, v53
	v_cvt_pk_bf16_f32 v53, v58, v59
	global_store_dwordx4 v[114:115], v[50:53], off offset:256
	v_pk_add_f32 v[40:41], v[40:41], v[226:227]
	v_pk_add_f32 v[38:39], v[38:39], v[224:225]
	v_pk_add_f32 v[50:51], v[44:45], v[230:231]
	v_pk_add_f32 v[44:45], v[42:43], v[228:229]
	v_cvt_pk_bf16_f32 v42, v46, v47
	v_cvt_pk_bf16_f32 v43, v48, v49
	v_pk_add_f32 v[32:33], v[32:33], v[226:227]
	v_cvt_pk_bf16_f32 v44, v44, v45
	v_cvt_pk_bf16_f32 v45, v50, v51
	global_store_dwordx4 v[106:107], v[42:45], off offset:256
	v_pk_add_f32 v[30:31], v[30:31], v[224:225]
	v_pk_add_f32 v[24:25], v[24:25], v[226:227]
	v_pk_add_f32 v[42:43], v[36:37], v[230:231]
	v_pk_add_f32 v[36:37], v[34:35], v[228:229]
	v_cvt_pk_bf16_f32 v34, v38, v39
	v_cvt_pk_bf16_f32 v35, v40, v41
	v_pk_add_f32 v[22:23], v[22:23], v[224:225]
	v_cvt_pk_bf16_f32 v36, v36, v37
	v_cvt_pk_bf16_f32 v37, v42, v43
	global_store_dwordx4 v[98:99], v[34:37], off offset:256
	v_pk_add_f32 v[16:17], v[16:17], v[226:227]
	v_pk_add_f32 v[14:15], v[14:15], v[224:225]
	v_pk_add_f32 v[34:35], v[28:29], v[230:231]
	v_pk_add_f32 v[28:29], v[26:27], v[228:229]
	v_cvt_pk_bf16_f32 v26, v30, v31
	v_cvt_pk_bf16_f32 v27, v32, v33
	v_pk_add_f32 v[6:7], v[6:7], v[224:225]
	v_cvt_pk_bf16_f32 v28, v28, v29
	v_cvt_pk_bf16_f32 v29, v34, v35
	global_store_dwordx4 v[90:91], v[26:29], off offset:256
	v_pk_add_f32 v[8:9], v[8:9], v[226:227]
	s_nop 0
	v_pk_add_f32 v[26:27], v[20:21], v[230:231]
	v_pk_add_f32 v[20:21], v[18:19], v[228:229]
	v_cvt_pk_bf16_f32 v18, v22, v23
	v_cvt_pk_bf16_f32 v19, v24, v25
	s_nop 0
	v_cvt_pk_bf16_f32 v20, v20, v21
	v_cvt_pk_bf16_f32 v21, v26, v27
	global_store_dwordx4 v[82:83], v[18:21], off offset:256
	s_nop 1
	v_pk_add_f32 v[18:19], v[12:13], v[230:231]
	v_pk_add_f32 v[12:13], v[10:11], v[228:229]
	v_cvt_pk_bf16_f32 v10, v14, v15
	v_cvt_pk_bf16_f32 v11, v16, v17
	s_nop 0
	v_cvt_pk_bf16_f32 v12, v12, v13
	v_cvt_pk_bf16_f32 v13, v18, v19
	global_store_dwordx4 v[74:75], v[10:13], off offset:256
	s_nop 1
	v_pk_add_f32 v[10:11], v[4:5], v[230:231]
	v_pk_add_f32 v[4:5], v[2:3], v[228:229]
	v_cvt_pk_bf16_f32 v2, v6, v7
	v_add_co_u32_e32 v6, vcc, 0x58000, v148
	v_cvt_pk_bf16_f32 v3, v8, v9
	v_cvt_pk_bf16_f32 v4, v4, v5
	v_cvt_pk_bf16_f32 v5, v10, v11
	s_nop 1
	v_addc_co_u32_e32 v7, vcc, 0, v149, vcc
	global_store_dwordx4 v[6:7], v[2:5], off offset:256
	s_andn2_b64 vcc, exec, s[10:11]
	s_mov_b64 s[10:11], -1
	s_cbranch_vccnz .LBB0_1045
	s_andn2_b64 vcc, exec, s[22:23]
	s_cbranch_vccnz .LBB0_1044
	s_barrier
	s_branch .LBB0_1044
